# cold-code compaction: SGU (gelu) GEMM epilogue row blocks 2..7 re-rolled into one copy of block 2's code run six times (accumulators/ssq moved into its registers, row offset in an SGPR), about 1000 fe
# speedup vs baseline: 1.0088x; 1.0006x over previous
.LBB0_145:
	s_mov_b32 s97, 0
	s_movk_i32 s96, 32
.Lmy_sg0_body:
	v_fmamk_f32 v1, v242, 0x3a800000, v233
	s_waitcnt lgkmcnt(0)
	v_mul_f32_e32 v133, 0x4b800000, v1
	v_cmp_gt_f32_e32 vcc, s61, v1
	v_add_u32_e32 v134, s96, v132
	v_ashrrev_i32_e32 v135, 31, v134
	v_cndmask_b32_e32 v1, v1, v133, vcc
	v_rsq_f32_e32 v1, v1
	v_lshlrev_b64 v[136:137], 12, v[134:135]
	v_lshl_add_u64 v[154:155], v[2:3], 0, v[136:137]
	v_mul_f32_e32 v133, 0x45800000, v1
	v_cndmask_b32_e32 v146, v1, v133, vcc
	v_pk_mul_f32 v[140:141], v[146:147], v[36:37] op_sel_hi:[0,1]
	v_pk_mul_f32 v[136:137], v[146:147], v[40:41] op_sel_hi:[0,1]
	v_mul_f32_e32 v133, 0x3d372713, v140
	v_fma_f32 v133, v140, v133, 1.0
	v_mul_f32_e32 v144, 0x3d372713, v137
	v_mul_f32_e32 v1, 0x3d372713, v136
	v_mul_f32_e32 v133, v140, v133
	v_fma_f32 v144, v137, v144, 1.0
	v_fma_f32 v1, v136, v1, 1.0
	v_mul_f32_e32 v133, 0xc0135761, v133
	v_mul_f32_e32 v144, v137, v144
	v_mul_f32_e32 v1, v136, v1
	v_exp_f32_e32 v133, v133
	v_mul_f32_e32 v144, 0xc0135761, v144
	v_mul_f32_e32 v1, 0xc0135761, v1
	v_exp_f32_e32 v144, v144
	v_exp_f32_e32 v1, v1
	v_add_f32_e32 v133, 1.0, v133
	v_rcp_f32_e32 v145, v133
	v_add_f32_e32 v133, 1.0, v144
	v_add_f32_e32 v1, 1.0, v1
	v_rcp_f32_e32 v144, v133
	v_mul_f32_e32 v133, 0x3d372713, v141
	v_rcp_f32_e32 v1, v1
	v_fma_f32 v133, v141, v133, 1.0
	v_mul_f32_e32 v133, v141, v133
	v_mul_f32_e32 v133, 0xc0135761, v133
	v_pk_mul_f32 v[138:139], v[146:147], v[42:43] op_sel_hi:[0,1]
	v_pk_mul_f32 v[142:143], v[146:147], v[38:39] op_sel_hi:[0,1]
	v_exp_f32_e32 v147, v133
	v_mul_f32_e32 v133, v136, v1
	v_mul_f32_e32 v136, v137, v144
	v_mul_f32_e32 v144, 0x3d372713, v142
	v_fma_f32 v144, v142, v144, 1.0
	v_mul_f32_e32 v144, v142, v144
	v_add_f32_e32 v137, 1.0, v147
	v_mul_f32_e32 v144, 0xc0135761, v144
	v_rcp_f32_e32 v137, v137
	v_exp_f32_e32 v144, v144
	v_mul_f32_e32 v1, v140, v145
	v_mul_f32_e32 v140, 0x3d372713, v138
	v_mul_f32_e32 v137, v141, v137
	v_add_f32_e32 v141, 1.0, v144
	v_mul_f32_e32 v144, 0x3d372713, v139
	v_mul_f32_e32 v145, 0x3d372713, v143
	v_fma_f32 v140, v138, v140, 1.0
	v_fma_f32 v144, v139, v144, 1.0
	v_fma_f32 v145, v143, v145, 1.0
	v_mul_f32_e32 v140, v138, v140
	v_mul_f32_e32 v144, v139, v144
	v_mul_f32_e32 v145, v143, v145
	v_mul_f32_e32 v140, 0xc0135761, v140
	v_mul_f32_e32 v144, 0xc0135761, v144
	v_mul_f32_e32 v145, 0xc0135761, v145
	v_exp_f32_e32 v140, v140
	v_exp_f32_e32 v144, v144
	v_exp_f32_e32 v145, v145
	v_rcp_f32_e32 v141, v141
	v_add_f32_e32 v140, 1.0, v140
	v_add_f32_e32 v144, 1.0, v144
	v_add_f32_e32 v145, 1.0, v145
	v_rcp_f32_e32 v140, v140
	v_rcp_f32_e32 v144, v144
	v_rcp_f32_e32 v145, v145
	v_pk_mul_f32 v[148:149], v[146:147], v[34:35] op_sel_hi:[0,1]
	v_mul_f32_e32 v140, v138, v140
	v_mul_f32_e32 v138, v142, v141
	v_mul_f32_e32 v141, v139, v144
	v_mul_f32_e32 v139, v143, v145
	v_cvt_pk_bf16_f32 v142, v133, v136
	v_cvt_pk_bf16_f32 v143, v140, v141
	v_cvt_pk_bf16_f32 v144, v1, v137
	v_cvt_pk_bf16_f32 v145, v138, v139
	global_store_dwordx4 v[154:155], v[142:145], off
	v_pk_mul_f32 v[150:151], v[146:147], v[30:31] op_sel_hi:[0,1]
	s_and_b64 vcc, exec, s[8:9]
	v_pk_mul_f32 v[144:145], v[146:147], v[32:33] op_sel_hi:[0,1]
	v_pk_mul_f32 v[146:147], v[146:147], v[28:29] op_sel_hi:[0,1]
	v_mul_f32_e32 v143, 0x3d372713, v146
	v_fma_f32 v143, v146, v143, 1.0
	v_mul_f32_e32 v152, 0x3d372713, v145
	v_mul_f32_e32 v142, 0x3d372713, v144
	v_mul_f32_e32 v143, v146, v143
	v_fma_f32 v152, v145, v152, 1.0
	v_fma_f32 v142, v144, v142, 1.0
	v_mul_f32_e32 v143, 0xc0135761, v143
	v_mul_f32_e32 v152, v145, v152
	v_mul_f32_e32 v142, v144, v142
	v_exp_f32_e32 v143, v143
	v_mul_f32_e32 v152, 0xc0135761, v152
	v_mul_f32_e32 v142, 0xc0135761, v142
	v_exp_f32_e32 v152, v152
	v_exp_f32_e32 v142, v142
	v_add_f32_e32 v143, 1.0, v143
	v_rcp_f32_e32 v153, v143
	v_add_f32_e32 v143, 1.0, v152
	v_add_f32_e32 v142, 1.0, v142
	v_rcp_f32_e32 v152, v143
	v_mul_f32_e32 v143, 0x3d372713, v147
	v_rcp_f32_e32 v142, v142
	v_fma_f32 v143, v147, v143, 1.0
	v_mul_f32_e32 v143, v147, v143
	v_mul_f32_e32 v143, 0xc0135761, v143
	v_exp_f32_e32 v156, v143
	v_mul_f32_e32 v143, v144, v142
	v_mul_f32_e32 v144, v145, v152
	v_mul_f32_e32 v152, 0x3d372713, v150
	v_fma_f32 v152, v150, v152, 1.0
	v_mul_f32_e32 v152, v150, v152
	v_add_f32_e32 v145, 1.0, v156
	v_mul_f32_e32 v152, 0xc0135761, v152
	v_rcp_f32_e32 v145, v145
	v_exp_f32_e32 v152, v152
	v_mul_f32_e32 v142, v146, v153
	v_mul_f32_e32 v146, 0x3d372713, v148
	v_mul_f32_e32 v145, v147, v145
	v_add_f32_e32 v147, 1.0, v152
	v_mul_f32_e32 v152, 0x3d372713, v149
	v_mul_f32_e32 v153, 0x3d372713, v151
	v_fma_f32 v146, v148, v146, 1.0
	v_fma_f32 v152, v149, v152, 1.0
	v_fma_f32 v153, v151, v153, 1.0
	v_mul_f32_e32 v146, v148, v146
	v_mul_f32_e32 v152, v149, v152
	v_mul_f32_e32 v153, v151, v153
	v_mul_f32_e32 v146, 0xc0135761, v146
	v_mul_f32_e32 v152, 0xc0135761, v152
	v_mul_f32_e32 v153, 0xc0135761, v153
	v_exp_f32_e32 v146, v146
	v_exp_f32_e32 v152, v152
	v_exp_f32_e32 v153, v153
	v_rcp_f32_e32 v147, v147
	v_add_f32_e32 v146, 1.0, v146
	v_add_f32_e32 v152, 1.0, v152
	v_add_f32_e32 v153, 1.0, v153
	v_rcp_f32_e32 v146, v146
	v_rcp_f32_e32 v152, v152
	v_rcp_f32_e32 v153, v153
	v_mul_f32_e32 v148, v148, v146
	v_mul_f32_e32 v146, v150, v147
	v_mul_f32_e32 v149, v149, v152
	v_mul_f32_e32 v147, v151, v153
	v_cvt_pk_bf16_f32 v150, v143, v144
	v_cvt_pk_bf16_f32 v151, v148, v149
	v_cvt_pk_bf16_f32 v152, v142, v145
	v_cvt_pk_bf16_f32 v153, v146, v147
	global_store_dwordx4 v[154:155], v[150:153], off offset:256
	s_cbranch_vccnz .Lmy_sg0_next
	v_mul_f32_e32 v136, v136, v136
	v_fmac_f32_e32 v136, v133, v133
	v_mul_f32_e32 v133, v141, v141
	v_fmac_f32_e32 v133, v140, v140
	v_add_f32_e32 v133, v136, v133
	v_mul_f32_e32 v136, v137, v137
	v_fmac_f32_e32 v136, v1, v1
	v_mul_f32_e32 v1, v139, v139
	v_fmac_f32_e32 v1, v138, v138
	v_add_f32_e32 v1, v136, v1
	v_add_f32_e32 v1, v1, v133
	v_mul_f32_e32 v133, v144, v144
	v_mul_f32_e32 v136, v149, v149
	v_fmac_f32_e32 v133, v143, v143
	v_fmac_f32_e32 v136, v148, v148
	v_add_f32_e32 v133, v133, v136
	v_mul_f32_e32 v136, v145, v145
	v_mul_f32_e32 v137, v147, v147
	v_fmac_f32_e32 v136, v142, v142
	v_fmac_f32_e32 v137, v146, v146
	v_add_f32_e32 v136, v136, v137
	v_add_f32_e32 v133, v136, v133
	v_add_f32_e32 v1, v133, v1
	ds_bpermute_b32 v133, v231, v1
	s_waitcnt lgkmcnt(0)
	v_add_f32_e32 v1, v1, v133
	ds_bpermute_b32 v133, v232, v1
	s_and_saveexec_b64 s[38:39], s[6:7]
	s_cbranch_execz .LBB0_148
	s_lshl_b32 s1, s18, 2
	v_readlane_b32 s42, v255, 22
	s_sub_i32 s40, s1, 32
	v_lshlrev_b64 v[134:135], 7, v[134:135]
	v_readlane_b32 s43, v255, 23
	s_ashr_i32 s41, s40, 31
	s_waitcnt lgkmcnt(0)
	v_add_f32_e32 v1, v1, v133
	v_lshl_add_u64 v[134:135], s[42:43], 0, v[134:135]
	v_lshl_add_u64 v[134:135], s[40:41], 2, v[134:135]
	s_lshl_b32 s40, s52, 2
	s_mov_b32 s41, s21
	v_lshl_add_u64 v[134:135], v[134:135], 0, s[40:41]
	global_store_dword v[134:135], v1, off

.Lmy_sg0_next:
	s_add_i32 s97, s97, 1
	s_cmp_eq_u32 s97, 1
	s_cbranch_scc1 .Lmy_sg0_set3
	s_cmp_eq_u32 s97, 2
	s_cbranch_scc1 .Lmy_sg0_set4
	s_cmp_eq_u32 s97, 3
	s_cbranch_scc1 .Lmy_sg0_set5
	s_cmp_eq_u32 s97, 4
	s_cbranch_scc1 .Lmy_sg0_set6
	s_cmp_eq_u32 s97, 5
	s_cbranch_scc1 .Lmy_sg0_set7
	s_branch .LBB0_169
.Lmy_sg0_set3:
	v_mov_b32_e32 v40, v24
	v_mov_b32_e32 v41, v25
	v_mov_b32_e32 v42, v26
	v_mov_b32_e32 v43, v27
	v_mov_b32_e32 v36, v20
	v_mov_b32_e32 v37, v21
	v_mov_b32_e32 v38, v22
	v_mov_b32_e32 v39, v23
	v_mov_b32_e32 v32, v16
	v_mov_b32_e32 v33, v17
	v_mov_b32_e32 v34, v18
	v_mov_b32_e32 v35, v19
	v_mov_b32_e32 v28, v4
	v_mov_b32_e32 v29, v5
	v_mov_b32_e32 v30, v6
	v_mov_b32_e32 v31, v7
	v_mov_b32_e32 v242, v241
	s_movk_i32 s96, 48
	s_branch .Lmy_sg0_body
.Lmy_sg0_set4:
	v_mov_b32_e32 v40, v128
	v_mov_b32_e32 v41, v129
	v_mov_b32_e32 v42, v130
	v_mov_b32_e32 v43, v131
	v_mov_b32_e32 v36, v124
	v_mov_b32_e32 v37, v125
	v_mov_b32_e32 v38, v126
	v_mov_b32_e32 v39, v127
	v_mov_b32_e32 v32, v120
	v_mov_b32_e32 v33, v121
	v_mov_b32_e32 v34, v122
	v_mov_b32_e32 v35, v123
	v_mov_b32_e32 v28, v116
	v_mov_b32_e32 v29, v117
	v_mov_b32_e32 v30, v118
	v_mov_b32_e32 v31, v119
	v_mov_b32_e32 v242, v240
	s_movk_i32 s96, 128
	s_branch .Lmy_sg0_body
.Lmy_sg0_set5:
	v_mov_b32_e32 v40, v112
	v_mov_b32_e32 v41, v113
	v_mov_b32_e32 v42, v114
	v_mov_b32_e32 v43, v115
	v_mov_b32_e32 v36, v108
	v_mov_b32_e32 v37, v109
	v_mov_b32_e32 v38, v110
	v_mov_b32_e32 v39, v111
	v_mov_b32_e32 v32, v104
	v_mov_b32_e32 v33, v105
	v_mov_b32_e32 v34, v106
	v_mov_b32_e32 v35, v107
	v_mov_b32_e32 v28, v100
	v_mov_b32_e32 v29, v101
	v_mov_b32_e32 v30, v102
	v_mov_b32_e32 v31, v103
	v_mov_b32_e32 v242, v239
	s_movk_i32 s96, 144
	s_branch .Lmy_sg0_body
.Lmy_sg0_set6:
	v_mov_b32_e32 v40, v96
	v_mov_b32_e32 v41, v97
	v_mov_b32_e32 v42, v98
	v_mov_b32_e32 v43, v99
	v_mov_b32_e32 v36, v92
	v_mov_b32_e32 v37, v93
	v_mov_b32_e32 v38, v94
	v_mov_b32_e32 v39, v95
	v_mov_b32_e32 v32, v88
	v_mov_b32_e32 v33, v89
	v_mov_b32_e32 v34, v90
	v_mov_b32_e32 v35, v91
	v_mov_b32_e32 v28, v84
	v_mov_b32_e32 v29, v85
	v_mov_b32_e32 v30, v86
	v_mov_b32_e32 v31, v87
	v_mov_b32_e32 v242, v238
	s_movk_i32 s96, 160
	s_branch .Lmy_sg0_body
.Lmy_sg0_set7:
	v_mov_b32_e32 v40, v80
	v_mov_b32_e32 v41, v81
	v_mov_b32_e32 v42, v82
	v_mov_b32_e32 v43, v83
	v_mov_b32_e32 v36, v76
	v_mov_b32_e32 v37, v77
	v_mov_b32_e32 v38, v78
	v_mov_b32_e32 v39, v79
	v_mov_b32_e32 v32, v12
	v_mov_b32_e32 v33, v13
	v_mov_b32_e32 v34, v14
	v_mov_b32_e32 v35, v15
	v_mov_b32_e32 v28, v8
	v_mov_b32_e32 v29, v9
	v_mov_b32_e32 v30, v10
	v_mov_b32_e32 v31, v11
	v_mov_b32_e32 v242, v219
	s_movk_i32 s96, 176
	s_branch .Lmy_sg0_body

.Lmy_sg1_body:
	v_fmamk_f32 v1, v242, 0x3a800000, v233
	s_waitcnt lgkmcnt(0)
	v_mul_f32_e32 v133, 0x4b800000, v1
	v_cmp_gt_f32_e32 vcc, s58, v1
	v_add_u32_e32 v134, s96, v132
	v_ashrrev_i32_e32 v135, 31, v134
	v_cndmask_b32_e32 v1, v1, v133, vcc
	v_rsq_f32_e32 v1, v1
	v_lshlrev_b64 v[136:137], 12, v[134:135]
	v_lshl_add_u64 v[154:155], v[2:3], 0, v[136:137]
	v_mul_f32_e32 v133, 0x45800000, v1
	v_cndmask_b32_e32 v146, v1, v133, vcc
	v_pk_mul_f32 v[140:141], v[146:147], v[36:37] op_sel_hi:[0,1]
	v_pk_mul_f32 v[136:137], v[146:147], v[40:41] op_sel_hi:[0,1]
	v_mul_f32_e32 v133, 0x3d372713, v140
	v_fma_f32 v133, v140, v133, 1.0
	v_mul_f32_e32 v144, 0x3d372713, v137
	v_mul_f32_e32 v1, 0x3d372713, v136
	v_mul_f32_e32 v133, v140, v133
	v_fma_f32 v144, v137, v144, 1.0
	v_fma_f32 v1, v136, v1, 1.0
	v_mul_f32_e32 v133, 0xc0135761, v133
	v_mul_f32_e32 v144, v137, v144
	v_mul_f32_e32 v1, v136, v1
	v_exp_f32_e32 v133, v133
	v_mul_f32_e32 v144, 0xc0135761, v144
	v_mul_f32_e32 v1, 0xc0135761, v1
	v_exp_f32_e32 v144, v144
	v_exp_f32_e32 v1, v1
	v_add_f32_e32 v133, 1.0, v133
	v_rcp_f32_e32 v145, v133
	v_add_f32_e32 v133, 1.0, v144
	v_add_f32_e32 v1, 1.0, v1
	v_rcp_f32_e32 v144, v133
	v_mul_f32_e32 v133, 0x3d372713, v141
	v_rcp_f32_e32 v1, v1
	v_fma_f32 v133, v141, v133, 1.0
	v_mul_f32_e32 v133, v141, v133
	v_mul_f32_e32 v133, 0xc0135761, v133
	v_pk_mul_f32 v[138:139], v[146:147], v[42:43] op_sel_hi:[0,1]
	v_pk_mul_f32 v[142:143], v[146:147], v[38:39] op_sel_hi:[0,1]
	v_exp_f32_e32 v147, v133
	v_mul_f32_e32 v133, v136, v1
	v_mul_f32_e32 v136, v137, v144
	v_mul_f32_e32 v144, 0x3d372713, v142
	v_fma_f32 v144, v142, v144, 1.0
	v_mul_f32_e32 v144, v142, v144
	v_add_f32_e32 v137, 1.0, v147
	v_mul_f32_e32 v144, 0xc0135761, v144
	v_rcp_f32_e32 v137, v137
	v_exp_f32_e32 v144, v144
	v_mul_f32_e32 v1, v140, v145
	v_mul_f32_e32 v140, 0x3d372713, v138
	v_mul_f32_e32 v137, v141, v137
	v_add_f32_e32 v141, 1.0, v144
	v_mul_f32_e32 v144, 0x3d372713, v139
	v_mul_f32_e32 v145, 0x3d372713, v143
	v_fma_f32 v140, v138, v140, 1.0
	v_fma_f32 v144, v139, v144, 1.0
	v_fma_f32 v145, v143, v145, 1.0
	v_mul_f32_e32 v140, v138, v140
	v_mul_f32_e32 v144, v139, v144
	v_mul_f32_e32 v145, v143, v145
	v_mul_f32_e32 v140, 0xc0135761, v140
	v_mul_f32_e32 v144, 0xc0135761, v144
	v_mul_f32_e32 v145, 0xc0135761, v145
	v_exp_f32_e32 v140, v140
	v_exp_f32_e32 v144, v144
	v_exp_f32_e32 v145, v145
	v_rcp_f32_e32 v141, v141
	v_add_f32_e32 v140, 1.0, v140
	v_add_f32_e32 v144, 1.0, v144
	v_add_f32_e32 v145, 1.0, v145
	v_rcp_f32_e32 v140, v140
	v_rcp_f32_e32 v144, v144
	v_rcp_f32_e32 v145, v145
	v_pk_mul_f32 v[148:149], v[146:147], v[34:35] op_sel_hi:[0,1]
	v_mul_f32_e32 v140, v138, v140
	v_mul_f32_e32 v138, v142, v141
	v_mul_f32_e32 v141, v139, v144
	v_mul_f32_e32 v139, v143, v145
	v_cvt_pk_bf16_f32 v142, v133, v136
	v_cvt_pk_bf16_f32 v143, v140, v141
	v_cvt_pk_bf16_f32 v144, v1, v137
	v_cvt_pk_bf16_f32 v145, v138, v139
	global_store_dwordx4 v[154:155], v[142:145], off
	v_pk_mul_f32 v[150:151], v[146:147], v[30:31] op_sel_hi:[0,1]
	s_and_b64 vcc, exec, s[14:15]
	v_pk_mul_f32 v[144:145], v[146:147], v[32:33] op_sel_hi:[0,1]
	v_pk_mul_f32 v[146:147], v[146:147], v[28:29] op_sel_hi:[0,1]
	v_mul_f32_e32 v143, 0x3d372713, v146
	v_fma_f32 v143, v146, v143, 1.0
	v_mul_f32_e32 v152, 0x3d372713, v145
	v_mul_f32_e32 v142, 0x3d372713, v144
	v_mul_f32_e32 v143, v146, v143
	v_fma_f32 v152, v145, v152, 1.0
	v_fma_f32 v142, v144, v142, 1.0
	v_mul_f32_e32 v143, 0xc0135761, v143
	v_mul_f32_e32 v152, v145, v152
	v_mul_f32_e32 v142, v144, v142
	v_exp_f32_e32 v143, v143
	v_mul_f32_e32 v152, 0xc0135761, v152
	v_mul_f32_e32 v142, 0xc0135761, v142
	v_exp_f32_e32 v152, v152
	v_exp_f32_e32 v142, v142
	v_add_f32_e32 v143, 1.0, v143
	v_rcp_f32_e32 v153, v143
	v_add_f32_e32 v143, 1.0, v152
	v_add_f32_e32 v142, 1.0, v142
	v_rcp_f32_e32 v152, v143
	v_mul_f32_e32 v143, 0x3d372713, v147
	v_rcp_f32_e32 v142, v142
	v_fma_f32 v143, v147, v143, 1.0
	v_mul_f32_e32 v143, v147, v143
	v_mul_f32_e32 v143, 0xc0135761, v143
	v_exp_f32_e32 v156, v143
	v_mul_f32_e32 v143, v144, v142
	v_mul_f32_e32 v144, v145, v152
	v_mul_f32_e32 v152, 0x3d372713, v150
	v_fma_f32 v152, v150, v152, 1.0
	v_mul_f32_e32 v152, v150, v152
	v_add_f32_e32 v145, 1.0, v156
	v_mul_f32_e32 v152, 0xc0135761, v152
	v_rcp_f32_e32 v145, v145
	v_exp_f32_e32 v152, v152
	v_mul_f32_e32 v142, v146, v153
	v_mul_f32_e32 v146, 0x3d372713, v148
	v_mul_f32_e32 v145, v147, v145
	v_add_f32_e32 v147, 1.0, v152
	v_mul_f32_e32 v152, 0x3d372713, v149
	v_mul_f32_e32 v153, 0x3d372713, v151
	v_fma_f32 v146, v148, v146, 1.0
	v_fma_f32 v152, v149, v152, 1.0
	v_fma_f32 v153, v151, v153, 1.0
	v_mul_f32_e32 v146, v148, v146
	v_mul_f32_e32 v152, v149, v152
	v_mul_f32_e32 v153, v151, v153
	v_mul_f32_e32 v146, 0xc0135761, v146
	v_mul_f32_e32 v152, 0xc0135761, v152
	v_mul_f32_e32 v153, 0xc0135761, v153
	v_exp_f32_e32 v146, v146
	v_exp_f32_e32 v152, v152
	v_exp_f32_e32 v153, v153
	v_rcp_f32_e32 v147, v147
	v_add_f32_e32 v146, 1.0, v146
	v_add_f32_e32 v152, 1.0, v152
	v_add_f32_e32 v153, 1.0, v153
	v_rcp_f32_e32 v146, v146
	v_rcp_f32_e32 v152, v152
	v_rcp_f32_e32 v153, v153
	v_mul_f32_e32 v148, v148, v146
	v_mul_f32_e32 v146, v150, v147
	v_mul_f32_e32 v149, v149, v152
	v_mul_f32_e32 v147, v151, v153
	v_cvt_pk_bf16_f32 v150, v143, v144
	v_cvt_pk_bf16_f32 v151, v148, v149
	v_cvt_pk_bf16_f32 v152, v142, v145
	v_cvt_pk_bf16_f32 v153, v146, v147
	global_store_dwordx4 v[154:155], v[150:153], off offset:256
	s_cbranch_vccnz .Lmy_sg1_next
	v_mul_f32_e32 v136, v136, v136
	v_fmac_f32_e32 v136, v133, v133
	v_mul_f32_e32 v133, v141, v141
	v_fmac_f32_e32 v133, v140, v140
	v_add_f32_e32 v133, v136, v133
	v_mul_f32_e32 v136, v137, v137
	v_fmac_f32_e32 v136, v1, v1
	v_mul_f32_e32 v1, v139, v139
	v_fmac_f32_e32 v1, v138, v138
	v_add_f32_e32 v1, v136, v1
	v_add_f32_e32 v1, v1, v133
	v_mul_f32_e32 v133, v144, v144
	v_mul_f32_e32 v136, v149, v149
	v_fmac_f32_e32 v133, v143, v143
	v_fmac_f32_e32 v136, v148, v148
	v_add_f32_e32 v133, v133, v136
	v_mul_f32_e32 v136, v145, v145
	v_mul_f32_e32 v137, v147, v147
	v_fmac_f32_e32 v136, v142, v142
	v_fmac_f32_e32 v137, v146, v146
	v_add_f32_e32 v136, v136, v137
	v_add_f32_e32 v133, v136, v133
	v_add_f32_e32 v1, v133, v1
	ds_bpermute_b32 v133, v231, v1
	s_waitcnt lgkmcnt(0)
	v_add_f32_e32 v1, v1, v133
	ds_bpermute_b32 v133, v232, v1
	s_and_saveexec_b64 s[8:9], s[12:13]
	s_cbranch_execz .LBB0_904
	s_lshl_b32 s1, s20, 2
	v_readlane_b32 s38, v255, 22
	s_sub_i32 s36, s1, 32
	v_lshlrev_b64 v[134:135], 7, v[134:135]
	v_readlane_b32 s39, v255, 23
	s_ashr_i32 s37, s36, 31
	s_waitcnt lgkmcnt(0)
	v_add_f32_e32 v1, v1, v133
	v_lshl_add_u64 v[134:135], s[38:39], 0, v[134:135]
	v_lshl_add_u64 v[134:135], s[36:37], 2, v[134:135]
	s_lshl_b32 s36, s50, 2
	s_mov_b32 s37, s23
	v_lshl_add_u64 v[134:135], v[134:135], 0, s[36:37]
	global_store_dword v[134:135], v1, off
